# v107 + S5 step C: waves 0..3 skip the 16 MFMAs of Toeplitz k-steps 8..15 (explicit zeros for their N-blocks; exact)
# baseline (speedup 1.0000x reference)
.LBB0_624:
	s_bitcmp1_b32 s24, 0
	s_cselect_b32 s50, 0, 0x8400
	s_cselect_b32 s25, 0x8400, 0
	s_add_i32 s50, s50, 0
	v_lshl_add_u64 v[0:1], s[20:21], 0, v[178:179]
	v_lshl_add_u64 v[2:3], s[20:21], 0, v[180:181]
	v_add3_u32 v99, s50, v212, v204
	v_lshl_add_u64 v[4:5], s[20:21], 0, v[182:183]
	v_lshl_add_u64 v[6:7], s[20:21], 0, v[184:185]
	global_load_dwordx4 v[100:103], v[0:1], off
	global_load_dwordx4 v[104:107], v[2:3], off
	global_load_dwordx4 v[108:111], v[4:5], off
	global_load_dwordx4 v[112:115], v[6:7], off
	s_waitcnt lgkmcnt(0)
	s_barrier
	ds_read_b128 v[0:3], v99
	ds_read_b128 v[16:19], v99 offset:32
	s_waitcnt vmcnt(19) lgkmcnt(1)
	v_mfma_f32_32x32x16_bf16 v[0:15], v[0:3], v[88:91], 0
	ds_read_b128 v[186:189], v99 offset:64
	ds_read_b128 v[190:193], v99 offset:96
	v_add_u32_e32 v220, s87, v208
	v_add_u32_e32 v229, 0, v208
	v_add_u32_e32 v223, s89, v208
	v_cndmask_b32_e64 v195, 0, v97, s[0:1]
	v_mul_f32_e32 v98, v155, v97
	v_mul_f32_e32 v194, v169, v97
	s_waitcnt vmcnt(18) lgkmcnt(2)
	v_mfma_f32_32x32x16_bf16 v[16:31], v[16:19], v[80:83], 0
	v_add_u32_e32 v229, 0x1cc00, v229
	v_cndmask_b32_e64 v232, 0, v96, s[0:1]
	v_fma_f32 v230, v154, v96, -v98
	v_fma_f32 v231, v155, v97, -v98
	s_mul_i32 s68, s96, 0x880
	v_add_u32_e32 v216, s68, v217
	v_add_u32_e32 v221, s49, v218
	v_add_u32_e32 v219, s95, v217
	s_waitcnt vmcnt(17) lgkmcnt(1)
	v_mfma_f32_32x32x16_bf16 v[0:15], v[186:189], v[68:71], v[0:15]
	v_add_u32_e32 v222, s94, v218
	v_add_u32_e32 v224, s91, v218
	v_add_u32_e32 v225, s26, v218
	v_add_u32_e32 v226, s27, v218
	v_add_u32_e32 v227, s3, v218
	v_add_u32_e32 v228, s33, v218
	s_add_i32 s25, s25, 0
	s_waitcnt vmcnt(16) lgkmcnt(0)
	v_mfma_f32_32x32x16_bf16 v[16:31], v[190:193], v[64:67], v[16:31]
	ds_read_b128 v[186:189], v99 offset:128
	ds_read_b128 v[190:193], v99 offset:160
	v_add3_u32 v233, s25, v214, v209
	v_add3_u32 v235, s50, v205, v204
	s_add_i32 s24, s24, 1
	v_lshl_add_u64 v[178:179], v[178:179], 0, s[76:77]
	v_lshl_add_u64 v[180:181], v[180:181], 0, s[76:77]
	v_lshl_add_u64 v[182:183], v[182:183], 0, s[76:77]
	s_waitcnt vmcnt(13) lgkmcnt(1)
	v_mfma_f32_32x32x16_bf16 v[0:15], v[186:189], v[92:95], v[0:15]
	v_lshl_add_u64 v[184:185], v[184:185], 0, s[76:77]
	s_cmp_lg_u32 s24, 8
	s_waitcnt lgkmcnt(0)
	v_mfma_f32_32x32x16_bf16 v[16:31], v[190:193], v[84:87], v[16:31]
	ds_read_b128 v[186:189], v99 offset:192
	ds_read_b128 v[190:193], v99 offset:224
	s_waitcnt lgkmcnt(1)
	v_mfma_f32_32x32x16_bf16 v[0:15], v[186:189], v[72:75], v[0:15]
	s_waitcnt vmcnt(8) lgkmcnt(0)
	v_mfma_f32_32x32x16_bf16 v[16:31], v[190:193], v[76:79], v[16:31]
	ds_read_b128 v[186:189], v99 offset:256
	ds_read_b128 v[190:193], v99 offset:288
	s_waitcnt lgkmcnt(1)
	v_mfma_f32_32x32x16_bf16 v[0:15], v[186:189], v[60:63], v[0:15]
	s_waitcnt lgkmcnt(0)
	v_mfma_f32_32x32x16_bf16 v[16:31], v[190:193], v[56:59], v[16:31]
	ds_read_b128 v[186:189], v99 offset:320
	ds_read_b128 v[190:193], v99 offset:352
	s_waitcnt lgkmcnt(1)
	v_mfma_f32_32x32x16_bf16 v[0:15], v[186:189], v[52:55], v[0:15]
	s_waitcnt lgkmcnt(0)
	v_mfma_f32_32x32x16_bf16 v[16:31], v[190:193], v[48:51], v[16:31]
	ds_read_b128 v[186:189], v99 offset:384
	ds_read_b128 v[190:193], v99 offset:416
	s_waitcnt vmcnt(7) lgkmcnt(1)
	v_mfma_f32_32x32x16_bf16 v[0:15], v[186:189], v[44:47], v[0:15]
	s_waitcnt vmcnt(6) lgkmcnt(0)
	v_mfma_f32_32x32x16_bf16 v[16:31], v[190:193], v[40:43], v[16:31]
	ds_read_b128 v[186:189], v99 offset:448
	ds_read_b128 v[190:193], v99 offset:480
	s_waitcnt vmcnt(5) lgkmcnt(1)
	v_mfma_f32_32x32x16_bf16 v[0:15], v[186:189], v[36:39], v[0:15]
	v_fma_f32 v186, v168, v96, v194
	v_fma_f32 v187, v169, v97, v194
	v_add3_u32 v188, s25, v210, v209
	v_add3_u32 v189, s25, v211, v209
	v_add3_u32 v194, s25, v213, v209
	s_waitcnt vmcnt(4) lgkmcnt(0)
	v_mfma_f32_32x32x16_bf16 v[16:31], v[190:193], v[32:35], v[16:31]
	s_nop 11
	v_add_f32_e32 v0, v0, v16
	v_add_f32_e32 v1, v1, v17
	v_add_f32_e32 v2, v2, v18
	v_add_f32_e32 v3, v3, v19
	v_add_f32_e32 v4, v4, v20
	v_add_f32_e32 v5, v5, v21
	v_add_f32_e32 v6, v6, v22
	v_add_f32_e32 v7, v7, v23
	v_add_f32_e32 v8, v8, v24
	v_add_f32_e32 v9, v9, v25
	v_add_f32_e32 v10, v10, v26
	v_add_f32_e32 v11, v11, v27
	v_add_f32_e32 v12, v12, v28
	v_add_f32_e32 v13, v13, v29
	v_add_f32_e32 v14, v14, v30
	v_add_f32_e32 v15, v15, v31
	ds_write2st64_b32 v215, v0, v1 offset1:2
	ds_write2st64_b32 v215, v2, v3 offset0:4 offset1:6
	ds_write2st64_b32 v215, v4, v5 offset0:16 offset1:18
	ds_write2st64_b32 v215, v6, v7 offset0:20 offset1:22
	ds_write2st64_b32 v215, v8, v9 offset0:32 offset1:34
	ds_write2st64_b32 v215, v10, v11 offset0:36 offset1:38
	ds_write2st64_b32 v215, v12, v13 offset0:48 offset1:50
	ds_write2st64_b32 v215, v14, v15 offset0:52 offset1:54
	s_waitcnt lgkmcnt(0)
	s_barrier
	ds_read2st64_b64 v[0:3], v220 offset1:1
	ds_read2st64_b64 v[4:7], v220 offset0:2 offset1:3
	ds_read2st64_b64 v[8:11], v220 offset0:4 offset1:5
	ds_read2st64_b64 v[12:15], v220 offset0:6 offset1:7
	s_waitcnt lgkmcnt(3)
	v_add_f32_e32 v16, v206, v1
	v_add_f32_e32 v0, v207, v0
	v_pk_mul_f32 v[16:17], v[166:167], v[16:17] op_sel_hi:[1,0]
	s_nop 0
	v_pk_fma_f32 v[18:19], v[136:137], v[0:1], v[16:17] neg_lo:[0,0,1] neg_hi:[0,0,1]
	v_pk_fma_f32 v[0:1], v[136:137], v[0:1], v[16:17] op_sel_hi:[1,0,1]
	s_nop 0
	v_mov_b32_e32 v19, v1
	v_pk_add_f32 v[0:1], v[2:3], v[18:19]
	s_nop 0
	v_mul_f32_e32 v2, v137, v1
	v_pk_mul_f32 v[16:17], v[136:137], v[0:1] op_sel:[0,1] op_sel_hi:[1,0]
	v_pk_fma_f32 v[0:1], v[136:137], v[0:1], v[2:3] op_sel_hi:[1,1,0] neg_lo:[0,0,1] neg_hi:[0,0,1]
	v_add_f32_e32 v2, v16, v17
	s_waitcnt lgkmcnt(2)
	v_pk_add_f32 v[2:3], v[4:5], v[2:3] op_sel:[1,0] op_sel_hi:[1,0]
	v_pk_add_f32 v[0:1], v[4:5], v[0:1]
	v_pk_mul_f32 v[2:3], v[136:137], v[2:3]
	s_nop 0
	v_pk_fma_f32 v[4:5], v[166:167], v[0:1], v[2:3]
	v_pk_fma_f32 v[0:1], v[166:167], v[0:1], v[2:3] op_sel_hi:[1,0,1] neg_lo:[0,0,1] neg_hi:[0,0,1]
	s_nop 0
	v_mov_b32_e32 v5, v1
	v_pk_add_f32 v[0:1], v[6:7], v[4:5] op_sel:[1,0] op_sel_hi:[0,1]
	v_mul_f32_e32 v2, v137, v0
	v_pk_mul_f32 v[4:5], v[136:137], v[0:1]
	v_pk_fma_f32 v[0:1], v[136:137], v[0:1], v[2:3] op_sel:[0,1,0] op_sel_hi:[1,0,0] neg_lo:[0,0,1] neg_hi:[0,0,1]
	v_add_f32_e32 v2, v4, v5
	s_waitcnt lgkmcnt(1)
	v_pk_add_f32 v[2:3], v[8:9], v[2:3] op_sel:[1,0] op_sel_hi:[1,0]
	v_pk_add_f32 v[0:1], v[8:9], v[0:1]
	v_pk_mul_f32 v[2:3], v[136:137], v[2:3]
	s_nop 0
	v_pk_fma_f32 v[4:5], v[166:167], v[0:1], v[2:3]
	v_pk_fma_f32 v[0:1], v[166:167], v[0:1], v[2:3] op_sel_hi:[1,0,1] neg_lo:[0,0,1] neg_hi:[0,0,1]
	s_nop 0
	v_mov_b32_e32 v5, v1
	v_pk_add_f32 v[0:1], v[10:11], v[4:5] op_sel:[1,0] op_sel_hi:[0,1]
	v_mul_f32_e32 v2, v137, v0
	v_pk_mul_f32 v[4:5], v[136:137], v[0:1]
	v_pk_fma_f32 v[0:1], v[136:137], v[0:1], v[2:3] op_sel:[0,1,0] op_sel_hi:[1,0,0] neg_lo:[0,0,1] neg_hi:[0,0,1]
	v_add_f32_e32 v2, v4, v5
	s_waitcnt lgkmcnt(0)
	v_pk_add_f32 v[2:3], v[12:13], v[2:3] op_sel:[1,0] op_sel_hi:[1,0]
	v_pk_add_f32 v[0:1], v[12:13], v[0:1]
	v_pk_mul_f32 v[2:3], v[166:167], v[2:3]
	s_nop 0
	v_pk_fma_f32 v[4:5], v[136:137], v[0:1], v[2:3] neg_lo:[0,0,1] neg_hi:[0,0,1]
	v_pk_fma_f32 v[0:1], v[136:137], v[0:1], v[2:3] op_sel_hi:[1,0,1]
	s_nop 0
	v_mov_b32_e32 v5, v1
	v_pk_add_f32 v[0:1], v[14:15], v[4:5]
	ds_write_b64 v223, v[0:1]
	s_waitcnt lgkmcnt(0)
	s_barrier
	global_load_dwordx4 v[18:21], v[156:157], off
	global_load_dwordx4 v[22:25], v[156:157], off offset:1024
	global_load_dwordx4 v[26:29], v[156:157], off offset:2048
	global_load_dwordx4 v[190:193], v[156:157], off offset:3072
	global_load_dwordx4 v[236:239], v[158:159], off
	global_load_dwordx4 v[240:243], v[160:161], off
	global_load_dwordx4 v[244:247], v[162:163], off
	global_load_dwordx4 v[248:251], v[164:165], off
	ds_read2st64_b64 v[0:3], v229 offset1:1
	ds_read2st64_b64 v[4:7], v229 offset0:2 offset1:3
	ds_read2st64_b64 v[8:11], v229 offset0:4 offset1:5
	ds_read2st64_b64 v[96:99], v229 offset0:6 offset1:7
	ds_read_b64 v[30:31], v221
	ds_read_b64 v[254:255], v222
	s_waitcnt lgkmcnt(3)
	v_pk_add_f32 v[12:13], v[230:231], v[0:1]
	v_pk_add_f32 v[0:1], v[186:187], v[0:1] op_sel:[0,1] op_sel_hi:[1,0]
	v_cndmask_b32_e64 v17, v232, v12, s[4:5]
	v_cndmask_b32_e64 v16, v195, v0, s[4:5]
	v_pk_mul_f32 v[0:1], v[168:169], v[0:1] op_sel_hi:[1,0]
	s_nop 0
	v_pk_fma_f32 v[14:15], v[154:155], v[12:13], v[0:1] neg_lo:[0,0,1] neg_hi:[0,0,1]
	v_pk_fma_f32 v[0:1], v[154:155], v[12:13], v[0:1] op_sel_hi:[1,0,1]
	s_nop 0
	v_mov_b32_e32 v15, v1
	v_pk_add_f32 v[0:1], v[2:3], v[14:15]
	s_nop 0
	v_cndmask_b32_e64 v13, v16, v1, s[6:7]
	v_mul_f32_e32 v2, v155, v1
	v_mul_f32_e32 v12, v155, v0
	v_cndmask_b32_e64 v14, v17, v0, s[6:7]
	v_pk_fma_f32 v[2:3], v[154:155], v[0:1], v[2:3] op_sel_hi:[1,1,0] neg_lo:[0,0,1] neg_hi:[0,0,1]
	v_pk_fma_f32 v[0:1], v[154:155], v[0:1], v[12:13] op_sel:[0,1,0] op_sel_hi:[1,0,0]
	s_waitcnt lgkmcnt(2)
	v_pk_add_f32 v[2:3], v[4:5], v[2:3]
	v_pk_add_f32 v[0:1], v[4:5], v[0:1] op_sel:[1,0] op_sel_hi:[0,1]
	v_cndmask_b32_e64 v12, v13, v0, s[8:9]
	v_pk_mul_f32 v[0:1], v[154:155], v[0:1] op_sel_hi:[1,0]
	v_cndmask_b32_e64 v13, v14, v2, s[8:9]
	v_pk_fma_f32 v[4:5], v[168:169], v[2:3], v[0:1]
	v_pk_fma_f32 v[0:1], v[168:169], v[2:3], v[0:1] op_sel_hi:[1,0,1] neg_lo:[0,0,1] neg_hi:[0,0,1]
	s_nop 0
	v_mov_b32_e32 v5, v1
	v_pk_add_f32 v[0:1], v[6:7], v[4:5] op_sel:[1,0] op_sel_hi:[0,1]
	v_cndmask_b32_e64 v5, v12, v0, s[10:11]
	v_mul_f32_e32 v2, v155, v0
	v_mul_f32_e32 v4, v155, v1
	v_cndmask_b32_e64 v6, v13, v1, s[10:11]
	v_pk_fma_f32 v[2:3], v[154:155], v[0:1], v[2:3] op_sel:[0,1,0] op_sel_hi:[1,0,0] neg_lo:[0,0,1] neg_hi:[0,0,1]
	v_pk_fma_f32 v[0:1], v[154:155], v[0:1], v[4:5] op_sel_hi:[1,1,0]
	s_waitcnt lgkmcnt(1)
	v_pk_add_f32 v[2:3], v[8:9], v[2:3]
	v_pk_add_f32 v[0:1], v[8:9], v[0:1] op_sel:[1,0] op_sel_hi:[0,1]
	v_cndmask_b32_e64 v7, v5, v0, s[12:13]
	v_pk_mul_f32 v[0:1], v[154:155], v[0:1] op_sel_hi:[1,0]
	v_cndmask_b32_e64 v6, v6, v2, s[12:13]
	v_pk_fma_f32 v[4:5], v[168:169], v[2:3], v[0:1]
	v_pk_fma_f32 v[0:1], v[168:169], v[2:3], v[0:1] op_sel_hi:[1,0,1] neg_lo:[0,0,1] neg_hi:[0,0,1]
	s_nop 0
	v_mov_b32_e32 v5, v1
	v_pk_add_f32 v[0:1], v[10:11], v[4:5] op_sel:[1,0] op_sel_hi:[0,1]
	v_cndmask_b32_e64 v5, v7, v0, s[14:15]
	v_mul_f32_e32 v2, v155, v0
	v_mul_f32_e32 v4, v155, v1
	v_cndmask_b32_e64 v6, v6, v1, s[14:15]
	v_pk_fma_f32 v[2:3], v[154:155], v[0:1], v[2:3] op_sel:[0,1,0] op_sel_hi:[1,0,0] neg_lo:[0,0,1] neg_hi:[0,0,1]
	v_pk_fma_f32 v[0:1], v[154:155], v[0:1], v[4:5] op_sel_hi:[1,1,0]
	s_waitcnt lgkmcnt(0)
	v_pk_add_f32 v[186:187], v[96:97], v[2:3]
	v_pk_add_f32 v[96:97], v[96:97], v[0:1] op_sel:[1,0] op_sel_hi:[0,1]
	v_cndmask_b32_e64 v0, v5, v96, s[16:17]
	v_cndmask_b32_e64 v1, v6, v186, s[16:17]
	v_cvt_pk_bf16_f32 v2, v1, v0
	v_mul_f32_e32 v3, v137, v0
	v_mul_f32_e32 v4, v137, v1
	ds_write_b32 v216, v2
	v_fma_f32 v2, v136, v1, -v3
	v_fmac_f32_e32 v4, v136, v0
	v_add_f32_e32 v0, v30, v2
	v_add_f32_e32 v1, v31, v4
	ds_read_b64 v[30:31], v224
	v_cvt_pk_bf16_f32 v2, v0, v1
	v_mul_f32_e32 v3, v137, v1
	v_mul_f32_e32 v4, v137, v0
	ds_write_b32 v219, v2
	v_fma_f32 v2, v136, v0, -v3
	v_fmac_f32_e32 v4, v136, v1
	v_add_f32_e32 v0, v254, v2
	v_add_f32_e32 v1, v255, v4
	ds_read_b64 v[254:255], v225
	v_cvt_pk_bf16_f32 v2, v0, v1
	v_mul_f32_e32 v3, v137, v1
	v_mul_f32_e32 v4, v137, v0
	ds_write_b32 v219, v2 offset:272
	v_fma_f32 v2, v136, v0, -v3
	v_fmac_f32_e32 v4, v136, v1
	s_waitcnt lgkmcnt(3)
	v_add_f32_e32 v0, v30, v2
	v_add_f32_e32 v1, v31, v4
	ds_read_b64 v[30:31], v226
	v_cvt_pk_bf16_f32 v2, v0, v1
	v_mul_f32_e32 v3, v137, v1
	v_mul_f32_e32 v4, v137, v0
	ds_write_b32 v219, v2 offset:544
	v_fma_f32 v2, v136, v0, -v3
	v_fmac_f32_e32 v4, v136, v1
	s_waitcnt lgkmcnt(3)
	v_add_f32_e32 v0, v254, v2
	v_add_f32_e32 v1, v255, v4
	ds_read_b64 v[254:255], v227
	v_cvt_pk_bf16_f32 v2, v0, v1
	v_mul_f32_e32 v3, v137, v1
	v_mul_f32_e32 v4, v137, v0
	ds_write_b32 v219, v2 offset:816
	v_fma_f32 v2, v136, v0, -v3
	v_fmac_f32_e32 v4, v136, v1
	s_waitcnt lgkmcnt(3)
	v_add_f32_e32 v0, v30, v2
	v_add_f32_e32 v1, v31, v4
	ds_read_b64 v[30:31], v228
	v_cvt_pk_bf16_f32 v2, v0, v1
	v_mul_f32_e32 v3, v137, v1
	v_mul_f32_e32 v4, v137, v0
	ds_write_b32 v219, v2 offset:1088
	v_fma_f32 v2, v136, v0, -v3
	v_fmac_f32_e32 v4, v136, v1
	s_waitcnt lgkmcnt(3)
	v_add_f32_e32 v0, v254, v2
	v_add_f32_e32 v1, v255, v4
	v_cvt_pk_bf16_f32 v2, v0, v1
	v_mul_f32_e32 v3, v137, v1
	v_mul_f32_e32 v4, v137, v0
	ds_write_b32 v219, v2 offset:1360
	v_fma_f32 v2, v136, v0, -v3
	v_fmac_f32_e32 v4, v136, v1
	s_waitcnt lgkmcnt(2)
	v_add_f32_e32 v0, v30, v2
	v_add_f32_e32 v1, v31, v4
	v_cvt_pk_bf16_f32 v0, v0, v1
	ds_write_b32 v216, v0 offset:1904
	s_waitcnt vmcnt(11)
	ds_write_b128 v188, v[100:103]
	s_waitcnt vmcnt(10)
	ds_write_b128 v189, v[104:107]
	s_waitcnt vmcnt(9)
	ds_write_b128 v194, v[108:111]
	s_waitcnt vmcnt(8)
	ds_write_b128 v233, v[112:115]
	s_waitcnt lgkmcnt(0)
	s_barrier
	v_cmp_gt_u32_e32 vcc, 0x100, v234
	s_waitcnt vmcnt(0)
	v_mov_b64_e32 v[16:17], v[18:19]
	v_mov_b64_e32 v[18:19], v[20:21]
	v_mov_b64_e32 v[100:101], v[22:23]
	v_mov_b64_e32 v[102:103], v[24:25]
	v_mov_b64_e32 v[104:105], v[26:27]
	v_mov_b64_e32 v[106:107], v[28:29]
	v_mov_b64_e32 v[108:109], v[190:191]
	v_mov_b64_e32 v[110:111], v[192:193]
	v_mov_b64_e32 v[112:113], v[236:237]
	v_mov_b64_e32 v[114:115], v[238:239]
	v_mov_b64_e32 v[188:189], v[240:241]
	v_mov_b64_e32 v[190:191], v[242:243]
	v_mov_b64_e32 v[192:193], v[244:245]
	v_mov_b64_e32 v[194:195], v[246:247]
	v_mov_b64_e32 v[230:231], v[248:249]
	v_mov_b64_e32 v[232:233], v[250:251]
	ds_read_b128 v[0:3], v235
	ds_read_b128 v[236:239], v235 offset:32
	s_waitcnt vmcnt(7) lgkmcnt(1)
	v_mfma_f32_32x32x16_bf16 v[0:15], v[0:3], v[16:19], 0
	ds_read_b128 v[20:23], v235 offset:16896
	ds_read_b128 v[240:243], v235 offset:16928
	s_waitcnt lgkmcnt(1)
	v_mfma_f32_32x32x16_bf16 v[16:31], v[20:23], v[16:19], 0
	s_waitcnt vmcnt(6)
	v_mfma_f32_32x32x16_bf16 v[0:15], v[236:239], v[100:103], v[0:15]
	s_waitcnt lgkmcnt(0)
	v_mfma_f32_32x32x16_bf16 v[16:31], v[240:243], v[100:103], v[16:31]
	ds_read_b128 v[100:103], v235 offset:64
	ds_read_b128 v[236:239], v235 offset:96
	s_waitcnt vmcnt(5) lgkmcnt(1)
	v_mfma_f32_32x32x16_bf16 v[0:15], v[100:103], v[104:107], v[0:15]
	ds_read_b128 v[100:103], v235 offset:16960
	ds_read_b128 v[240:243], v235 offset:16992
	s_waitcnt lgkmcnt(1)
	v_mfma_f32_32x32x16_bf16 v[16:31], v[100:103], v[104:107], v[16:31]
	ds_read_b128 v[100:103], v235 offset:128
	ds_read_b128 v[104:107], v235 offset:160
	s_waitcnt vmcnt(4)
	v_mfma_f32_32x32x16_bf16 v[0:15], v[236:239], v[108:111], v[0:15]
	s_waitcnt lgkmcnt(2)
	v_mfma_f32_32x32x16_bf16 v[16:31], v[240:243], v[108:111], v[16:31]
	s_waitcnt vmcnt(3) lgkmcnt(1)
	v_mfma_f32_32x32x16_bf16 v[0:15], v[100:103], v[112:115], v[0:15]
	ds_read_b128 v[100:103], v235 offset:17024
	ds_read_b128 v[108:111], v235 offset:17056
	s_waitcnt lgkmcnt(1)
	v_mfma_f32_32x32x16_bf16 v[16:31], v[100:103], v[112:115], v[16:31]
	global_load_dwordx4 v[100:103], v[152:153], off
	ds_read_b128 v[112:115], v235 offset:224
	s_waitcnt vmcnt(3)
	v_mfma_f32_32x32x16_bf16 v[0:15], v[104:107], v[188:191], v[0:15]
	ds_read_b128 v[104:107], v235 offset:192
	s_waitcnt lgkmcnt(2)
	v_mfma_f32_32x32x16_bf16 v[16:31], v[108:111], v[188:191], v[16:31]
	global_load_dwordx4 v[108:111], v[150:151], off
	s_waitcnt vmcnt(3) lgkmcnt(0)
	v_mfma_f32_32x32x16_bf16 v[0:15], v[104:107], v[192:195], v[0:15]
	ds_read_b128 v[104:107], v235 offset:17088
	ds_read_b128 v[188:191], v235 offset:17120
	s_waitcnt lgkmcnt(1)
	v_mfma_f32_32x32x16_bf16 v[16:31], v[104:107], v[192:195], v[16:31]
	global_load_dwordx4 v[104:107], v[148:149], off
	s_waitcnt vmcnt(3)
	v_mfma_f32_32x32x16_bf16 v[0:15], v[112:115], v[230:233], v[0:15]
	global_load_dwordx4 v[112:115], v[140:141], off
	global_load_dwordx4 v[192:195], v[138:139], off
	global_load_dwordx4 v[236:239], v[142:143], off
	global_load_dwordx4 v[240:243], v[144:145], off
	global_load_dwordx4 v[244:247], v[146:147], off
	s_waitcnt lgkmcnt(0)
	v_mfma_f32_32x32x16_bf16 v[16:31], v[188:191], v[230:233], v[16:31]
	ds_read_b128 v[188:191], v235 offset:256
	ds_read_b128 v[230:233], v235 offset:288
	s_waitcnt vmcnt(7) lgkmcnt(1)
	s_cbranch_vccnz .Lmy_zkl_0
	v_mfma_f32_32x32x16_bf16 v[0:15], v[188:191], v[100:103], v[0:15]
.Lmy_zkl_0:
	ds_read_b128 v[188:191], v235 offset:17152
	ds_read_b128 v[248:251], v235 offset:17184
	s_waitcnt lgkmcnt(1)
	s_cbranch_vccnz .Lmy_zkl_1
	v_mfma_f32_32x32x16_bf16 v[16:31], v[188:191], v[100:103], v[16:31]
.Lmy_zkl_1:
	s_waitcnt vmcnt(6)
	s_cbranch_vccnz .Lmy_zkl_2
	v_mfma_f32_32x32x16_bf16 v[0:15], v[230:233], v[108:111], v[0:15]
.Lmy_zkl_2:
	s_waitcnt lgkmcnt(0)
	s_cbranch_vccnz .Lmy_zkl_3
	v_mfma_f32_32x32x16_bf16 v[16:31], v[248:251], v[108:111], v[16:31]
.Lmy_zkl_3:
	ds_read_b128 v[100:103], v235 offset:320
	ds_read_b128 v[108:111], v235 offset:352
	s_waitcnt vmcnt(5) lgkmcnt(1)
	s_cbranch_vccnz .Lmy_zkl_4
	v_mfma_f32_32x32x16_bf16 v[0:15], v[100:103], v[104:107], v[0:15]
.Lmy_zkl_4:
	ds_read_b128 v[100:103], v235 offset:17216
	ds_read_b128 v[188:191], v235 offset:17248
	s_waitcnt lgkmcnt(1)
	s_cbranch_vccnz .Lmy_zkl_5
	v_mfma_f32_32x32x16_bf16 v[16:31], v[100:103], v[104:107], v[16:31]
.Lmy_zkl_5:
	ds_read_b128 v[100:103], v235 offset:384
	ds_read_b128 v[104:107], v235 offset:416
	s_waitcnt vmcnt(4)
	s_cbranch_vccnz .Lmy_zkl_6
	v_mfma_f32_32x32x16_bf16 v[0:15], v[108:111], v[112:115], v[0:15]
.Lmy_zkl_6:
	s_waitcnt lgkmcnt(2)
	s_cbranch_vccnz .Lmy_zkl_7
	v_mfma_f32_32x32x16_bf16 v[16:31], v[188:191], v[112:115], v[16:31]
.Lmy_zkl_7:
	s_waitcnt vmcnt(3) lgkmcnt(1)
	s_cbranch_vccnz .Lmy_zkl_8
	v_mfma_f32_32x32x16_bf16 v[0:15], v[100:103], v[192:195], v[0:15]
.Lmy_zkl_8:
	ds_read_b128 v[100:103], v235 offset:17280
	ds_read_b128 v[108:111], v235 offset:17312
	global_load_dwordx4 v[112:115], v[126:127], off
	global_load_dwordx4 v[188:191], v[126:127], off offset:1024
	s_waitcnt lgkmcnt(1)
	s_cbranch_vccnz .Lmy_zkl_9
	v_mfma_f32_32x32x16_bf16 v[16:31], v[100:103], v[192:195], v[16:31]
.Lmy_zkl_9:
	ds_read_b128 v[100:103], v235 offset:448
	s_waitcnt vmcnt(4)
	s_cbranch_vccnz .Lmy_zkl_10
	v_mfma_f32_32x32x16_bf16 v[0:15], v[104:107], v[236:239], v[0:15]
.Lmy_zkl_10:
	ds_read_b128 v[104:107], v235 offset:480
	s_waitcnt vmcnt(3) lgkmcnt(1)
	s_cbranch_vccnz .Lmy_zkl_11
	v_mfma_f32_32x32x16_bf16 v[0:15], v[100:103], v[240:243], v[0:15]
.Lmy_zkl_11:
	ds_read_b128 v[100:103], v235 offset:17344
	ds_read_b128 v[192:195], v235 offset:17376
	global_load_dwordx4 v[230:233], v[126:127], off offset:2048
	s_cbranch_vccnz .Lmy_zkl_12
	v_mfma_f32_32x32x16_bf16 v[16:31], v[108:111], v[236:239], v[16:31]
.Lmy_zkl_12:
	s_waitcnt lgkmcnt(1)
	s_cbranch_vccnz .Lmy_zkl_13
	v_mfma_f32_32x32x16_bf16 v[16:31], v[100:103], v[240:243], v[16:31]
.Lmy_zkl_13:
	s_waitcnt vmcnt(3)
	s_cbranch_vccnz .Lmy_zkl_14
	v_mfma_f32_32x32x16_bf16 v[0:15], v[104:107], v[244:247], v[0:15]
.Lmy_zkl_14:
	global_load_dwordx4 v[236:239], v[126:127], off offset:3072
	global_load_dwordx4 v[240:243], v[128:129], off
	global_load_dwordx4 v[108:111], v[130:131], off
	global_load_dwordx4 v[104:107], v[132:133], off
	global_load_dwordx4 v[100:103], v[134:135], off
	s_waitcnt lgkmcnt(0)
	s_cbranch_vccnz .Lmy_zkl_15
	v_mfma_f32_32x32x16_bf16 v[16:31], v[192:195], v[244:247], v[16:31]
.Lmy_zkl_15:
	ds_read_b128 v[192:195], v116
	ds_read_b128 v[244:247], v116 offset:32
	s_waitcnt vmcnt(7) lgkmcnt(1)
	v_mfma_f32_32x32x16_bf16 v[0:15], v[192:195], v[112:115], v[0:15]
	ds_read_b128 v[192:195], v116 offset:8704
	ds_read_b128 v[248:251], v116 offset:8736
	s_waitcnt lgkmcnt(1)
	v_mfma_f32_32x32x16_bf16 v[16:31], v[192:195], v[112:115], v[16:31]
	s_waitcnt vmcnt(6)
	v_mfma_f32_32x32x16_bf16 v[0:15], v[244:247], v[188:191], v[0:15]
	s_waitcnt lgkmcnt(0)
	v_mfma_f32_32x32x16_bf16 v[16:31], v[248:251], v[188:191], v[16:31]
	ds_read_b128 v[112:115], v116 offset:64
	ds_read_b128 v[188:191], v116 offset:96
	s_waitcnt vmcnt(5) lgkmcnt(1)
	v_mfma_f32_32x32x16_bf16 v[0:15], v[112:115], v[230:233], v[0:15]
	ds_read_b128 v[112:115], v116 offset:8768
	ds_read_b128 v[192:195], v116 offset:8800
	s_waitcnt lgkmcnt(1)
	v_mfma_f32_32x32x16_bf16 v[16:31], v[112:115], v[230:233], v[16:31]
	s_waitcnt vmcnt(4)
	v_mfma_f32_32x32x16_bf16 v[0:15], v[188:191], v[236:239], v[0:15]
	ds_read_b128 v[112:115], v116 offset:128
	ds_read_b128 v[188:191], v116 offset:160
	s_waitcnt lgkmcnt(2)
	v_mfma_f32_32x32x16_bf16 v[16:31], v[192:195], v[236:239], v[16:31]
	s_waitcnt vmcnt(3) lgkmcnt(1)
	v_mfma_f32_32x32x16_bf16 v[0:15], v[112:115], v[240:243], v[0:15]
	ds_read_b128 v[192:195], v116 offset:8832
	ds_read_b128 v[112:115], v116 offset:8864
	s_waitcnt lgkmcnt(1)
	v_mfma_f32_32x32x16_bf16 v[16:31], v[192:195], v[240:243], v[16:31]
	v_lshl_add_u64 v[192:193], s[20:21], 0, v[172:173]
	v_lshl_add_u64 v[194:195], s[20:21], 0, v[170:171]
	v_lshl_add_u64 v[170:171], v[170:171], 0, s[66:67]
	v_lshl_add_u64 v[172:173], v[172:173], 0, s[66:67]
	s_waitcnt vmcnt(2)
	v_mfma_f32_32x32x16_bf16 v[0:15], v[188:191], v[108:111], v[0:15]
	v_lshl_add_u64 v[188:189], s[20:21], 0, v[176:177]
	v_lshl_add_u64 v[190:191], s[20:21], 0, v[174:175]
	v_lshl_add_u64 v[174:175], v[174:175], 0, s[66:67]
	v_lshl_add_u64 v[176:177], v[176:177], 0, s[66:67]
	s_waitcnt lgkmcnt(0)
	v_mfma_f32_32x32x16_bf16 v[16:31], v[112:115], v[108:111], v[16:31]
	ds_read_b128 v[108:111], v116 offset:192
	ds_read_b128 v[112:115], v116 offset:224
	s_waitcnt vmcnt(1) lgkmcnt(1)
	v_mfma_f32_32x32x16_bf16 v[0:15], v[108:111], v[104:107], v[0:15]
	ds_read_b128 v[230:233], v116 offset:8896
	ds_read_b128 v[108:111], v116 offset:8928
	s_waitcnt lgkmcnt(1)
	v_mfma_f32_32x32x16_bf16 v[16:31], v[230:233], v[104:107], v[16:31]
	v_mul_f32_e64 v104, v168, v96
	v_mul_f32_e64 v105, v169, v96
	v_fma_f32 v96, v154, v186, -v104
	v_fma_f32 v97, v155, v187, -v105
	v_fma_f32 v104, v154, v186, v104
	v_fma_f32 v105, v155, v186, v105
	v_mov_b32_e32 v97, v105
	v_pk_add_f32 v[96:97], v[98:99], v[96:97]
	s_waitcnt vmcnt(0)
	v_mfma_f32_32x32x16_bf16 v[0:15], v[112:115], v[100:103], v[0:15]
	s_waitcnt lgkmcnt(0)
	v_mfma_f32_32x32x16_bf16 v[16:31], v[108:111], v[100:103], v[16:31]
	s_nop 9
	v_mul_f32_e32 v100, v0, v0
	v_fmamk_f32 v100, v100, 0xbdd2d3e8, v197
	v_mul_f32_e32 v102, v1, v1
	v_mul_f32_e32 v100, v0, v100
	v_mul_f32_e32 v104, v2, v2
	v_fmamk_f32 v102, v102, 0xbdd2d3e8, v197
	v_exp_f32_e32 v100, v100
	v_mul_f32_e32 v101, v16, v16
	v_mul_f32_e32 v103, v17, v17
	v_fmamk_f32 v101, v101, 0xbdd2d3e8, v197
	v_mul_f32_e32 v105, v18, v18
	v_fmamk_f32 v103, v103, 0xbdd2d3e8, v197
	v_mul_f32_e32 v101, v16, v101
	v_mul_f32_e32 v106, v3, v3
	v_mul_f32_e32 v107, v19, v19
	v_fmamk_f32 v104, v104, 0xbdd2d3e8, v197
	v_fmamk_f32 v105, v105, 0xbdd2d3e8, v197
	v_mul_f32_e32 v102, v1, v102
	v_mul_f32_e32 v103, v17, v103
	v_exp_f32_e32 v101, v101
	v_mul_f32_e32 v108, v4, v4
	v_mul_f32_e32 v109, v20, v20
	v_fmamk_f32 v106, v106, 0xbdd2d3e8, v197
	v_fmamk_f32 v107, v107, 0xbdd2d3e8, v197
	v_mul_f32_e32 v104, v2, v104
	v_mul_f32_e32 v105, v18, v105
	v_exp_f32_e32 v102, v102
	v_exp_f32_e32 v103, v103
	v_mul_f32_e32 v110, v5, v5
	v_mul_f32_e32 v111, v21, v21
	v_fmamk_f32 v108, v108, 0xbdd2d3e8, v197
	v_fmamk_f32 v109, v109, 0xbdd2d3e8, v197
	v_mul_f32_e32 v106, v3, v106
	v_mul_f32_e32 v107, v19, v107
	v_exp_f32_e32 v104, v104
	v_exp_f32_e32 v105, v105
	v_mul_f32_e32 v112, v6, v6
	v_mul_f32_e32 v113, v22, v22
	v_fmamk_f32 v110, v110, 0xbdd2d3e8, v197
	v_fmamk_f32 v111, v111, 0xbdd2d3e8, v197
	v_mul_f32_e32 v108, v4, v108
	v_mul_f32_e32 v109, v20, v109
	v_exp_f32_e32 v106, v106
	v_exp_f32_e32 v107, v107
	v_add_f32_e32 v100, 1.0, v100
	v_mul_f32_e32 v114, v7, v7
	v_mul_f32_e32 v115, v23, v23
	v_fmamk_f32 v112, v112, 0xbdd2d3e8, v197
	v_fmamk_f32 v113, v113, 0xbdd2d3e8, v197
	v_mul_f32_e32 v110, v5, v110
	v_mul_f32_e32 v111, v21, v111
	v_exp_f32_e32 v108, v108
	v_exp_f32_e32 v109, v109
	v_add_f32_e32 v101, 1.0, v101
	v_rcp_f32_e32 v100, v100
	v_mul_f32_e32 v186, v8, v8
	v_mul_f32_e32 v187, v24, v24
	v_fmamk_f32 v114, v114, 0xbdd2d3e8, v197
	v_fmamk_f32 v115, v115, 0xbdd2d3e8, v197
	v_mul_f32_e32 v112, v6, v112
	v_mul_f32_e32 v113, v22, v113
	v_exp_f32_e32 v110, v110
	v_exp_f32_e32 v111, v111
	v_add_f32_e32 v102, 1.0, v102
	v_add_f32_e32 v103, 1.0, v103
	v_rcp_f32_e32 v101, v101
	v_mul_f32_e32 v230, v9, v9
	v_mul_f32_e32 v231, v25, v25
	v_fmamk_f32 v186, v186, 0xbdd2d3e8, v197
	v_fmamk_f32 v187, v187, 0xbdd2d3e8, v197
	v_mul_f32_e32 v114, v7, v114
	v_mul_f32_e32 v115, v23, v115
	v_exp_f32_e32 v112, v112
	v_exp_f32_e32 v113, v113
	v_add_f32_e32 v104, 1.0, v104
	v_add_f32_e32 v105, 1.0, v105
	v_rcp_f32_e32 v102, v102
	v_rcp_f32_e32 v103, v103
	v_mul_f32_e32 v232, v10, v10
	v_mul_f32_e32 v233, v26, v26
	v_fmamk_f32 v230, v230, 0xbdd2d3e8, v197
	v_fmamk_f32 v231, v231, 0xbdd2d3e8, v197
	v_mul_f32_e32 v186, v8, v186
	v_mul_f32_e32 v187, v24, v187
	v_exp_f32_e32 v114, v114
	v_exp_f32_e32 v115, v115
	v_add_f32_e32 v106, 1.0, v106
	v_add_f32_e32 v107, 1.0, v107
	v_rcp_f32_e32 v104, v104
	v_rcp_f32_e32 v105, v105
	v_mul_f32_e32 v235, v11, v11
	v_mul_f32_e32 v236, v27, v27
	v_fmamk_f32 v232, v232, 0xbdd2d3e8, v197
	v_fmamk_f32 v233, v233, 0xbdd2d3e8, v197
	v_mul_f32_e32 v230, v9, v230
	v_mul_f32_e32 v231, v25, v231
	v_exp_f32_e32 v186, v186
	v_exp_f32_e32 v187, v187
	v_add_f32_e32 v108, 1.0, v108
	v_add_f32_e32 v109, 1.0, v109
	v_rcp_f32_e32 v106, v106
	v_rcp_f32_e32 v107, v107
	v_mul_f32_e32 v0, v0, v100
	v_mul_f32_e32 v237, v12, v12
	v_mul_f32_e32 v238, v28, v28
	v_fmamk_f32 v235, v235, 0xbdd2d3e8, v197
	v_fmamk_f32 v236, v236, 0xbdd2d3e8, v197
	v_mul_f32_e32 v232, v10, v232
	v_mul_f32_e32 v233, v26, v233
	v_exp_f32_e32 v230, v230
	v_exp_f32_e32 v231, v231
	v_add_f32_e32 v110, 1.0, v110
	v_add_f32_e32 v111, 1.0, v111
	v_rcp_f32_e32 v108, v108
	v_rcp_f32_e32 v109, v109
	v_mul_f32_e32 v16, v16, v101
	v_cvt_pk_bf16_f32 v0, v0, v16
	v_mul_f32_e32 v239, v13, v13
	v_mul_f32_e32 v240, v29, v29
	v_fmamk_f32 v237, v237, 0xbdd2d3e8, v197
	v_fmamk_f32 v238, v238, 0xbdd2d3e8, v197
	v_mul_f32_e32 v235, v11, v235
	v_mul_f32_e32 v236, v27, v236
	v_exp_f32_e32 v232, v232
	v_exp_f32_e32 v233, v233
	v_add_f32_e32 v112, 1.0, v112
	v_add_f32_e32 v113, 1.0, v113
	v_rcp_f32_e32 v110, v110
	v_rcp_f32_e32 v111, v111
	v_mul_f32_e32 v1, v1, v102
	v_mul_f32_e32 v17, v17, v103
	ds_write_b16 v198, v0
	ds_write_b16_d16_hi v198, v0 offset:16384
	v_cvt_pk_bf16_f32 v0, v1, v17
	v_mul_f32_e32 v241, v14, v14
	v_mul_f32_e32 v242, v30, v30
	v_fmamk_f32 v239, v239, 0xbdd2d3e8, v197
	v_fmamk_f32 v240, v240, 0xbdd2d3e8, v197
	v_mul_f32_e32 v237, v12, v237
	v_mul_f32_e32 v238, v28, v238
	v_exp_f32_e32 v235, v235
	v_exp_f32_e32 v236, v236
	v_add_f32_e32 v114, 1.0, v114
	v_add_f32_e32 v115, 1.0, v115
	v_rcp_f32_e32 v112, v112
	v_rcp_f32_e32 v113, v113
	v_mul_f32_e32 v2, v2, v104
	v_mul_f32_e32 v18, v18, v105
	ds_write_b16 v198, v0 offset:512
	ds_write_b16_d16_hi v198, v0 offset:16896
	v_cvt_pk_bf16_f32 v0, v2, v18
	v_mul_f32_e32 v243, v15, v15
	v_mul_f32_e32 v244, v31, v31
	v_fmamk_f32 v241, v241, 0xbdd2d3e8, v197
	v_fmamk_f32 v242, v242, 0xbdd2d3e8, v197
	v_mul_f32_e32 v239, v13, v239
	v_mul_f32_e32 v240, v29, v240
	v_exp_f32_e32 v237, v237
	v_exp_f32_e32 v238, v238
	v_add_f32_e32 v186, 1.0, v186
	v_add_f32_e32 v187, 1.0, v187
	v_rcp_f32_e32 v114, v114
	v_rcp_f32_e32 v115, v115
	v_mul_f32_e32 v3, v3, v106
	v_mul_f32_e32 v19, v19, v107
	ds_write_b16 v198, v0 offset:1024
	ds_write_b16_d16_hi v198, v0 offset:17408
	v_cvt_pk_bf16_f32 v0, v3, v19
	v_fmamk_f32 v243, v243, 0xbdd2d3e8, v197
	v_fmamk_f32 v244, v244, 0xbdd2d3e8, v197
	v_mul_f32_e32 v241, v14, v241
	v_mul_f32_e32 v242, v30, v242
	v_exp_f32_e32 v239, v239
	v_exp_f32_e32 v240, v240
	v_add_f32_e32 v230, 1.0, v230
	v_add_f32_e32 v231, 1.0, v231
	v_rcp_f32_e32 v186, v186
	v_rcp_f32_e32 v187, v187
	v_mul_f32_e32 v4, v4, v108
	v_mul_f32_e32 v20, v20, v109
	ds_write_b16 v198, v0 offset:1536
	ds_write_b16_d16_hi v198, v0 offset:17920
	v_cvt_pk_bf16_f32 v0, v4, v20
	v_mul_f32_e32 v243, v15, v243
	v_mul_f32_e32 v244, v31, v244
	v_exp_f32_e32 v241, v241
	v_exp_f32_e32 v242, v242
	v_add_f32_e32 v232, 1.0, v232
	v_add_f32_e32 v233, 1.0, v233
	v_rcp_f32_e32 v230, v230
	v_rcp_f32_e32 v231, v231
	v_mul_f32_e32 v5, v5, v110
	v_mul_f32_e32 v21, v21, v111
	ds_write_b16 v198, v0 offset:4096
	ds_write_b16_d16_hi v198, v0 offset:20480
	v_cvt_pk_bf16_f32 v0, v5, v21
	v_exp_f32_e32 v243, v243
	v_exp_f32_e32 v244, v244
	v_add_f32_e32 v235, 1.0, v235
	v_add_f32_e32 v236, 1.0, v236
	v_rcp_f32_e32 v232, v232
	v_rcp_f32_e32 v233, v233
	v_mul_f32_e32 v6, v6, v112
	v_mul_f32_e32 v22, v22, v113
	ds_write_b16 v198, v0 offset:4608
	ds_write_b16_d16_hi v198, v0 offset:20992
	v_cvt_pk_bf16_f32 v0, v6, v22
	v_add_f32_e32 v237, 1.0, v237
	v_add_f32_e32 v238, 1.0, v238
	v_rcp_f32_e32 v235, v235
	v_rcp_f32_e32 v236, v236
	v_mul_f32_e32 v7, v7, v114
	v_mul_f32_e32 v23, v23, v115
	ds_write_b16 v198, v0 offset:5120
	ds_write_b16_d16_hi v198, v0 offset:21504
	v_cvt_pk_bf16_f32 v0, v7, v23
	v_add_f32_e32 v239, 1.0, v239
	v_add_f32_e32 v240, 1.0, v240
	v_rcp_f32_e32 v237, v237
	v_rcp_f32_e32 v238, v238
	v_mul_f32_e32 v8, v8, v186
	v_mul_f32_e32 v24, v24, v187
	ds_write_b16 v198, v0 offset:5632
	ds_write_b16_d16_hi v198, v0 offset:22016
	v_cvt_pk_bf16_f32 v0, v8, v24
	v_add_f32_e32 v241, 1.0, v241
	v_add_f32_e32 v242, 1.0, v242
	v_rcp_f32_e32 v239, v239
	v_rcp_f32_e32 v240, v240
	v_mul_f32_e32 v9, v9, v230
	v_mul_f32_e32 v25, v25, v231
	ds_write_b16 v198, v0 offset:8192
	ds_write_b16_d16_hi v198, v0 offset:24576
	v_cvt_pk_bf16_f32 v0, v9, v25
	v_add_f32_e32 v243, 1.0, v243
	v_add_f32_e32 v244, 1.0, v244
	v_rcp_f32_e32 v241, v241
	v_rcp_f32_e32 v242, v242
	v_mul_f32_e32 v10, v10, v232
	v_mul_f32_e32 v26, v26, v233
	ds_write_b16 v198, v0 offset:8704
	ds_write_b16_d16_hi v198, v0 offset:25088
	v_cvt_pk_bf16_f32 v0, v10, v26
	v_rcp_f32_e32 v243, v243
	v_rcp_f32_e32 v244, v244
	v_mul_f32_e32 v11, v11, v235
	v_mul_f32_e32 v27, v27, v236
	ds_write_b16 v198, v0 offset:9216
	ds_write_b16_d16_hi v198, v0 offset:25600
	v_cvt_pk_bf16_f32 v0, v11, v27
	v_mul_f32_e32 v12, v12, v237
	v_mul_f32_e32 v28, v28, v238
	ds_write_b16 v198, v0 offset:9728
	ds_write_b16_d16_hi v198, v0 offset:26112
	v_cvt_pk_bf16_f32 v0, v12, v28
	v_mul_f32_e32 v13, v13, v239
	v_mul_f32_e32 v29, v29, v240
	ds_write_b16 v198, v0 offset:12288
	ds_write_b16_d16_hi v198, v0 offset:28672
	v_cvt_pk_bf16_f32 v0, v13, v29
	v_mul_f32_e32 v14, v14, v241
	v_mul_f32_e32 v30, v30, v242
	ds_write_b16 v198, v0 offset:12800
	ds_write_b16_d16_hi v198, v0 offset:29184
	v_cvt_pk_bf16_f32 v0, v14, v30
	v_mul_f32_e32 v15, v15, v243
	v_mul_f32_e32 v31, v31, v244
	ds_write_b16 v198, v0 offset:13312
	ds_write_b16_d16_hi v198, v0 offset:29696
	v_cvt_pk_bf16_f32 v0, v15, v31
	ds_write_b16 v198, v0 offset:13824
	ds_write_b16_d16_hi v198, v0 offset:30208
	s_waitcnt lgkmcnt(0)
	s_barrier
	ds_read_b128 v[0:3], v202
	ds_read_b128 v[4:7], v201
	ds_read_b128 v[8:11], v200
	ds_read_b128 v[12:15], v199
	s_waitcnt lgkmcnt(3)
	global_store_dwordx4 v[188:189], v[0:3], off
	s_waitcnt lgkmcnt(2)
	global_store_dwordx4 v[190:191], v[4:7], off
	s_waitcnt lgkmcnt(1)
	global_store_dwordx4 v[192:193], v[8:11], off
	s_waitcnt lgkmcnt(0)
	global_store_dwordx4 v[194:195], v[12:15], off
	s_cbranch_scc1 .LBB0_624
	v_add3_u32 v98, 0, v212, v204
	s_barrier
	ds_read_b128 v[0:3], v98 offset:33792
	ds_read_b128 v[16:19], v98 offset:33824
	s_waitcnt lgkmcnt(1)
	v_mfma_f32_32x32x16_bf16 v[0:15], v[0:3], v[88:91], 0
	s_lshl_b32 s2, s2, 24
	s_add_u32 s2, s20, s2
	s_addc_u32 s25, s21, 0
	s_add_u32 s24, s2, s78
	s_addc_u32 s25, s25, s79
	s_waitcnt lgkmcnt(0)
	v_mfma_f32_32x32x16_bf16 v[16:31], v[16:19], v[80:83], 0
	ds_read_b128 v[80:83], v98 offset:33856
	ds_read_b128 v[88:91], v98 offset:33888
	s_waitcnt lgkmcnt(1)
	v_mfma_f32_32x32x16_bf16 v[0:15], v[80:83], v[68:71], v[0:15]
	s_waitcnt lgkmcnt(0)
	v_mfma_f32_32x32x16_bf16 v[16:31], v[88:91], v[64:67], v[16:31]
	ds_read_b128 v[64:67], v98 offset:33920
	ds_read_b128 v[68:71], v98 offset:33952
	s_waitcnt lgkmcnt(1)
	v_mfma_f32_32x32x16_bf16 v[0:15], v[64:67], v[92:95], v[0:15]
	s_waitcnt lgkmcnt(0)
	v_mfma_f32_32x32x16_bf16 v[16:31], v[68:71], v[84:87], v[16:31]
	ds_read_b128 v[64:67], v98 offset:33984
	ds_read_b128 v[68:71], v98 offset:34016
	s_waitcnt lgkmcnt(1)
	v_mfma_f32_32x32x16_bf16 v[0:15], v[64:67], v[72:75], v[0:15]
	s_waitcnt lgkmcnt(0)
	v_mfma_f32_32x32x16_bf16 v[16:31], v[68:71], v[76:79], v[16:31]
	ds_read_b128 v[64:67], v98 offset:34048
	ds_read_b128 v[68:71], v98 offset:34080
	v_add3_u32 v76, 0, v205, v204
	s_waitcnt lgkmcnt(1)
	v_mfma_f32_32x32x16_bf16 v[0:15], v[64:67], v[60:63], v[0:15]
	s_waitcnt lgkmcnt(0)
	v_mfma_f32_32x32x16_bf16 v[16:31], v[68:71], v[56:59], v[16:31]
	ds_read_b128 v[56:59], v98 offset:34112
	ds_read_b128 v[60:63], v98 offset:34144
	s_waitcnt lgkmcnt(1)
	v_mfma_f32_32x32x16_bf16 v[0:15], v[56:59], v[52:55], v[0:15]
	s_waitcnt lgkmcnt(0)
	v_mfma_f32_32x32x16_bf16 v[16:31], v[60:63], v[48:51], v[16:31]
	ds_read_b128 v[48:51], v98 offset:34176
	ds_read_b128 v[52:55], v98 offset:34208
	s_waitcnt lgkmcnt(1)
	v_mfma_f32_32x32x16_bf16 v[0:15], v[48:51], v[44:47], v[0:15]
	s_waitcnt lgkmcnt(0)
	v_mfma_f32_32x32x16_bf16 v[16:31], v[52:55], v[40:43], v[16:31]
	ds_read_b128 v[40:43], v98 offset:34240
	ds_read_b128 v[44:47], v98 offset:34272
	s_waitcnt lgkmcnt(1)
	v_mfma_f32_32x32x16_bf16 v[0:15], v[40:43], v[36:39], v[0:15]
	s_waitcnt lgkmcnt(0)
	v_mfma_f32_32x32x16_bf16 v[16:31], v[44:47], v[32:35], v[16:31]
	s_nop 11
	v_add_f32_e32 v0, v0, v16
	v_add_f32_e32 v1, v1, v17
	ds_write2st64_b32 v215, v0, v1 offset1:2
	v_add_f32_e32 v0, v2, v18
	v_add_f32_e32 v1, v3, v19
	ds_write2st64_b32 v215, v0, v1 offset0:4 offset1:6
	v_add_f32_e32 v0, v4, v20
	v_add_f32_e32 v1, v5, v21
	ds_write2st64_b32 v215, v0, v1 offset0:16 offset1:18
	v_add_f32_e32 v0, v6, v22
	v_add_f32_e32 v1, v7, v23
	ds_write2st64_b32 v215, v0, v1 offset0:20 offset1:22
	v_add_f32_e32 v0, v8, v24
	v_add_f32_e32 v1, v9, v25
	ds_write2st64_b32 v215, v0, v1 offset0:32 offset1:34
	v_add_f32_e32 v0, v10, v26
	v_add_f32_e32 v1, v11, v27
	ds_write2st64_b32 v215, v0, v1 offset0:36 offset1:38
	v_add_f32_e32 v0, v12, v28
	v_add_f32_e32 v1, v13, v29
	ds_write2st64_b32 v215, v0, v1 offset0:48 offset1:50
	v_add_f32_e32 v0, v14, v30
	v_add_f32_e32 v1, v15, v31
	ds_write2st64_b32 v215, v0, v1 offset0:52 offset1:54
	s_waitcnt lgkmcnt(0)
	s_barrier
	global_load_dwordx4 v[16:19], v[156:157], off
	global_load_dwordx4 v[32:35], v[156:157], off offset:1024
	global_load_dwordx4 v[36:39], v[156:157], off offset:2048
	global_load_dwordx4 v[40:43], v[156:157], off offset:3072
	global_load_dwordx4 v[44:47], v[158:159], off
	global_load_dwordx4 v[48:51], v[160:161], off
	global_load_dwordx4 v[52:55], v[162:163], off
	global_load_dwordx4 v[56:59], v[164:165], off
	global_load_dwordx4 v[78:81], v[152:153], off
	global_load_dwordx4 v[82:85], v[150:151], off
	global_load_dwordx4 v[86:89], v[148:149], off
	global_load_dwordx4 v[90:93], v[140:141], off
	global_load_dwordx4 v[100:103], v[138:139], off
	global_load_dwordx4 v[104:107], v[142:143], off
	global_load_dwordx4 v[108:111], v[144:145], off
	global_load_dwordx4 v[112:115], v[146:147], off
	global_load_dwordx4 v[168:171], v[126:127], off
	global_load_dwordx4 v[172:175], v[126:127], off offset:1024
	global_load_dwordx4 v[176:179], v[126:127], off offset:2048
	global_load_dwordx4 v[180:183], v[126:127], off offset:3072
	global_load_dwordx4 v[184:187], v[128:129], off
	global_load_dwordx4 v[188:191], v[130:131], off
	global_load_dwordx4 v[192:195], v[132:133], off
	global_load_dwordx4 v[236:239], v[134:135], off
	ds_read2st64_b64 v[0:3], v220 offset1:1
	ds_read2st64_b64 v[4:7], v220 offset0:2 offset1:3
	s_waitcnt lgkmcnt(1)
	v_add_f32_e32 v8, v206, v1
	v_add_f32_e32 v0, v207, v0
	v_pk_mul_f32 v[8:9], v[166:167], v[8:9] op_sel_hi:[1,0]
	s_nop 0
	v_pk_fma_f32 v[10:11], v[136:137], v[0:1], v[8:9] neg_lo:[0,0,1] neg_hi:[0,0,1]
	v_pk_fma_f32 v[0:1], v[136:137], v[0:1], v[8:9] op_sel_hi:[1,0,1]
	s_nop 0
	v_mov_b32_e32 v11, v1
	v_pk_add_f32 v[0:1], v[2:3], v[10:11]
	s_nop 0
	v_mul_f32_e32 v2, v137, v1
	v_pk_mul_f32 v[10:11], v[136:137], v[0:1] op_sel:[0,1] op_sel_hi:[1,0]
	v_pk_fma_f32 v[2:3], v[136:137], v[0:1], v[2:3] op_sel_hi:[1,1,0] neg_lo:[0,0,1] neg_hi:[0,0,1]
	v_add_f32_e32 v10, v10, v11
	s_waitcnt lgkmcnt(0)
	v_pk_add_f32 v[8:9], v[4:5], v[2:3]
	v_pk_add_f32 v[4:5], v[4:5], v[10:11] op_sel:[1,0] op_sel_hi:[1,0]
	ds_read2st64_b64 v[0:3], v220 offset0:4 offset1:5
	v_pk_mul_f32 v[4:5], v[136:137], v[4:5]
	s_nop 0
	v_pk_fma_f32 v[10:11], v[166:167], v[8:9], v[4:5]
	v_pk_fma_f32 v[4:5], v[166:167], v[8:9], v[4:5] op_sel_hi:[1,0,1] neg_lo:[0,0,1] neg_hi:[0,0,1]
	s_nop 0
	v_mov_b32_e32 v11, v5
	v_pk_add_f32 v[8:9], v[6:7], v[10:11] op_sel:[1,0] op_sel_hi:[0,1]
	v_mul_f32_e32 v4, v137, v8
	v_pk_fma_f32 v[10:11], v[136:137], v[8:9], v[4:5] op_sel:[0,1,0] op_sel_hi:[1,0,0] neg_lo:[0,0,1] neg_hi:[0,0,1]
	v_pk_mul_f32 v[8:9], v[136:137], v[8:9]
	ds_read2st64_b64 v[4:7], v220 offset0:6 offset1:7
	v_add_f32_e32 v8, v8, v9
	s_waitcnt lgkmcnt(1)
	v_pk_add_f32 v[10:11], v[0:1], v[10:11]
	v_pk_add_f32 v[0:1], v[0:1], v[8:9] op_sel:[1,0] op_sel_hi:[1,0]
	s_nop 0
	v_pk_mul_f32 v[0:1], v[136:137], v[0:1]
	s_nop 0
	v_pk_fma_f32 v[8:9], v[166:167], v[10:11], v[0:1]
	v_pk_fma_f32 v[0:1], v[166:167], v[10:11], v[0:1] op_sel_hi:[1,0,1] neg_lo:[0,0,1] neg_hi:[0,0,1]
	s_nop 0
	v_mov_b32_e32 v9, v1
	v_pk_add_f32 v[0:1], v[2:3], v[8:9] op_sel:[1,0] op_sel_hi:[0,1]
	v_mul_f32_e32 v2, v137, v0
	v_pk_fma_f32 v[2:3], v[136:137], v[0:1], v[2:3] op_sel:[0,1,0] op_sel_hi:[1,0,0] neg_lo:[0,0,1] neg_hi:[0,0,1]
	v_pk_mul_f32 v[0:1], v[136:137], v[0:1]
	s_waitcnt lgkmcnt(0)
	v_pk_add_f32 v[2:3], v[4:5], v[2:3]
	v_add_f32_e32 v0, v0, v1
	v_pk_add_f32 v[0:1], v[4:5], v[0:1] op_sel:[1,0] op_sel_hi:[1,0]
	v_cndmask_b32_e64 v8, 0, v97, s[0:1]
	v_pk_mul_f32 v[0:1], v[166:167], v[0:1]
	v_cndmask_b32_e64 v9, 0, v96, s[0:1]
	v_pk_fma_f32 v[4:5], v[136:137], v[2:3], v[0:1] neg_lo:[0,0,1] neg_hi:[0,0,1]
	v_pk_fma_f32 v[0:1], v[136:137], v[2:3], v[0:1] op_sel_hi:[1,0,1]
	s_nop 0
	v_mov_b32_e32 v5, v1
	v_pk_add_f32 v[0:1], v[6:7], v[4:5]
	ds_write_b64 v223, v[0:1]
	s_waitcnt lgkmcnt(0)
	s_barrier
	ds_read2st64_b64 v[0:3], v229 offset1:1
	v_pk_mul_f32 v[4:5], v[154:155], v[96:97]
	s_nop 0
	v_sub_f32_e32 v10, v4, v5
	ds_read2st64_b64 v[4:7], v229 offset0:2 offset1:3
	s_waitcnt lgkmcnt(1)
	v_add_f32_e32 v0, v10, v0
	v_mul_f32_e32 v10, v154, v97
	v_fmac_f32_e32 v10, v155, v96
	v_add_f32_e32 v1, v10, v1
	v_mul_f32_e32 v10, v154, v0
	v_cndmask_b32_e64 v8, v8, v1, s[4:5]
	v_fma_f32 v10, -v155, v1, v10
	v_mul_f32_e32 v1, v154, v1
	v_fmac_f32_e32 v1, v155, v0
	v_cndmask_b32_e64 v9, v9, v0, s[4:5]
	v_add_f32_e32 v2, v2, v10
	v_add_f32_e32 v0, v3, v1
	v_cndmask_b32_e64 v1, v8, v0, s[6:7]
	v_mul_f32_e32 v8, v154, v2
	v_fma_f32 v8, -v155, v0, v8
	v_mul_f32_e32 v0, v154, v0
	s_waitcnt lgkmcnt(0)
	v_add_f32_e32 v4, v4, v8
	v_fmac_f32_e32 v0, v155, v2
	v_cndmask_b32_e64 v3, v9, v2, s[6:7]
	v_add_f32_e32 v0, v5, v0
	v_mul_f32_e32 v2, v154, v4
	v_cndmask_b32_e64 v1, v1, v0, s[8:9]
	v_fma_f32 v2, -v155, v0, v2
	v_mul_f32_e32 v0, v154, v0
	v_fmac_f32_e32 v0, v155, v4
	v_add_f32_e32 v7, v7, v0
	v_cndmask_b32_e64 v5, v3, v4, s[8:9]
	v_add_f32_e32 v6, v6, v2
	v_cndmask_b32_e64 v8, v1, v7, s[10:11]
	ds_read2st64_b64 v[0:3], v229 offset0:4 offset1:5
	v_mul_f32_e32 v4, v154, v6
	v_fma_f32 v10, -v155, v7, v4
	v_mul_f32_e32 v7, v154, v7
	v_fmac_f32_e32 v7, v155, v6
	v_cndmask_b32_e64 v9, v5, v6, s[10:11]
	ds_read_b64 v[4:5], v229 offset:3072
	s_waitcnt lgkmcnt(1)
	v_add_f32_e32 v0, v0, v10
	v_add_f32_e32 v1, v1, v7
	v_cndmask_b32_e64 v6, v8, v1, s[12:13]
	v_mul_f32_e32 v8, v154, v0
	v_fma_f32 v8, -v155, v1, v8
	v_mul_f32_e32 v1, v154, v1
	v_fmac_f32_e32 v1, v155, v0
	v_cndmask_b32_e64 v7, v9, v0, s[12:13]
	v_add_f32_e32 v2, v2, v8
	v_add_f32_e32 v0, v3, v1
	v_cndmask_b32_e64 v1, v6, v0, s[14:15]
	v_mul_f32_e32 v6, v154, v2
	v_fma_f32 v6, -v155, v0, v6
	v_mul_f32_e32 v0, v154, v0
	v_fmac_f32_e32 v0, v155, v2
	v_cndmask_b32_e64 v3, v7, v2, s[14:15]
	s_waitcnt lgkmcnt(0)
	v_add_f32_e32 v4, v4, v6
	v_add_f32_e32 v0, v5, v0
	v_cndmask_b32_e64 v2, v1, v0, s[16:17]
	v_cndmask_b32_e64 v3, v3, v4, s[16:17]
	v_cvt_pk_bf16_f32 v0, v3, v2
	ds_write_b32 v216, v0
	ds_read_b64 v[0:1], v221
	v_mul_f32_e32 v4, v137, v2
	v_fma_f32 v4, v136, v3, -v4
	s_waitcnt lgkmcnt(0)
	v_add_f32_e32 v4, v0, v4
	v_mul_f32_e32 v0, v137, v3
	v_fmac_f32_e32 v0, v136, v2
	v_add_f32_e32 v2, v1, v0
	v_cvt_pk_bf16_f32 v0, v4, v2
	ds_write_b32 v219, v0
	ds_read_b64 v[0:1], v222
	v_mul_f32_e32 v3, v137, v2
	v_fma_f32 v3, v136, v4, -v3
	s_waitcnt lgkmcnt(0)
	v_add_f32_e32 v3, v0, v3
	v_mul_f32_e32 v0, v137, v4
	v_fmac_f32_e32 v0, v136, v2
	v_add_f32_e32 v2, v1, v0
	v_cvt_pk_bf16_f32 v0, v3, v2
	ds_write_b32 v219, v0 offset:272
	ds_read_b64 v[0:1], v224
	v_mul_f32_e32 v4, v137, v2
	v_fma_f32 v4, v136, v3, -v4
	s_waitcnt lgkmcnt(0)
	v_add_f32_e32 v4, v0, v4
	v_mul_f32_e32 v0, v137, v3
	v_fmac_f32_e32 v0, v136, v2
	v_add_f32_e32 v2, v1, v0
	v_cvt_pk_bf16_f32 v0, v4, v2
	ds_write_b32 v219, v0 offset:544
	ds_read_b64 v[0:1], v225
	v_mul_f32_e32 v3, v137, v2
	v_fma_f32 v3, v136, v4, -v3
	s_waitcnt lgkmcnt(0)
	v_add_f32_e32 v3, v0, v3
	v_mul_f32_e32 v0, v137, v4
	v_fmac_f32_e32 v0, v136, v2
	v_add_f32_e32 v2, v1, v0
	v_cvt_pk_bf16_f32 v0, v3, v2
	ds_write_b32 v219, v0 offset:816
	ds_read_b64 v[0:1], v226
	v_mul_f32_e32 v4, v137, v2
	v_fma_f32 v4, v136, v3, -v4
	s_waitcnt lgkmcnt(0)
	v_add_f32_e32 v4, v0, v4
	v_mul_f32_e32 v0, v137, v3
	v_fmac_f32_e32 v0, v136, v2
	v_add_f32_e32 v2, v1, v0
	v_cvt_pk_bf16_f32 v0, v4, v2
	ds_write_b32 v219, v0 offset:1088
	ds_read_b64 v[0:1], v227
	v_mul_f32_e32 v3, v137, v2
	v_fma_f32 v3, v136, v4, -v3
	s_waitcnt lgkmcnt(0)
	v_add_f32_e32 v3, v0, v3
	v_mul_f32_e32 v0, v137, v4
	v_fmac_f32_e32 v0, v136, v2
	v_add_f32_e32 v2, v1, v0
	v_cvt_pk_bf16_f32 v0, v3, v2
	ds_write_b32 v219, v0 offset:1360
	ds_read_b64 v[0:1], v228
	v_mul_f32_e32 v4, v137, v2
	v_fma_f32 v4, v136, v3, -v4
	v_mul_f32_e32 v3, v137, v3
	v_fmac_f32_e32 v3, v136, v2
	s_waitcnt lgkmcnt(0)
	v_add_f32_e32 v0, v0, v4
	v_add_f32_e32 v1, v1, v3
	v_cvt_pk_bf16_f32 v0, v0, v1
	ds_write_b32 v216, v0 offset:1904
	s_waitcnt lgkmcnt(0)
	s_barrier
	s_waitcnt vmcnt(0)
	v_cmp_gt_u32_e32 vcc, 0x100, v234
	ds_read_b128 v[0:3], v76 offset:33792
	ds_read_b128 v[60:63], v76 offset:33824
	s_waitcnt vmcnt(7) lgkmcnt(1)
	v_mfma_f32_32x32x16_bf16 v[0:15], v[0:3], v[16:19], 0
	ds_read_b128 v[20:23], v76 offset:50688
	ds_read_b128 v[64:67], v76 offset:50720
	s_waitcnt lgkmcnt(1)
	v_mfma_f32_32x32x16_bf16 v[16:31], v[20:23], v[16:19], 0
	s_waitcnt vmcnt(6)
	v_mfma_f32_32x32x16_bf16 v[0:15], v[60:63], v[32:35], v[0:15]
	s_waitcnt lgkmcnt(0)
	v_mfma_f32_32x32x16_bf16 v[16:31], v[64:67], v[32:35], v[16:31]
	ds_read_b128 v[32:35], v76 offset:33856
	ds_read_b128 v[60:63], v76 offset:33888
	s_waitcnt vmcnt(5) lgkmcnt(1)
	v_mfma_f32_32x32x16_bf16 v[0:15], v[32:35], v[36:39], v[0:15]
	ds_read_b128 v[32:35], v76 offset:50752
	ds_read_b128 v[64:67], v76 offset:50784
	s_waitcnt lgkmcnt(1)
	v_mfma_f32_32x32x16_bf16 v[16:31], v[32:35], v[36:39], v[16:31]
	ds_read_b128 v[32:35], v76 offset:33920
	ds_read_b128 v[36:39], v76 offset:33952
	s_waitcnt vmcnt(4)
	v_mfma_f32_32x32x16_bf16 v[0:15], v[60:63], v[40:43], v[0:15]
	s_waitcnt lgkmcnt(2)
	v_mfma_f32_32x32x16_bf16 v[16:31], v[64:67], v[40:43], v[16:31]
	s_waitcnt vmcnt(3) lgkmcnt(1)
	v_mfma_f32_32x32x16_bf16 v[0:15], v[32:35], v[44:47], v[0:15]
	ds_read_b128 v[32:35], v76 offset:50816
	ds_read_b128 v[40:43], v76 offset:50848
	s_waitcnt lgkmcnt(1)
	v_mfma_f32_32x32x16_bf16 v[16:31], v[32:35], v[44:47], v[16:31]
	ds_read_b128 v[44:47], v76 offset:34016
	s_waitcnt vmcnt(3)
	v_mfma_f32_32x32x16_bf16 v[0:15], v[36:39], v[48:51], v[0:15]
	ds_read_b128 v[36:39], v76 offset:33984
	s_waitcnt lgkmcnt(2)
	v_mfma_f32_32x32x16_bf16 v[16:31], v[40:43], v[48:51], v[16:31]
	s_waitcnt vmcnt(3) lgkmcnt(0)
	v_mfma_f32_32x32x16_bf16 v[0:15], v[36:39], v[52:55], v[0:15]
	ds_read_b128 v[36:39], v76 offset:50880
	ds_read_b128 v[48:51], v76 offset:50912
	s_waitcnt lgkmcnt(1)
	v_mfma_f32_32x32x16_bf16 v[16:31], v[36:39], v[52:55], v[16:31]
	s_waitcnt vmcnt(3)
	v_mfma_f32_32x32x16_bf16 v[0:15], v[44:47], v[56:59], v[0:15]
	s_waitcnt lgkmcnt(0)
	v_mfma_f32_32x32x16_bf16 v[16:31], v[48:51], v[56:59], v[16:31]
	ds_read_b128 v[48:51], v76 offset:34048
	ds_read_b128 v[56:59], v76 offset:34080
	s_waitcnt vmcnt(7) lgkmcnt(1)
	s_cbranch_vccnz .Lmy_zkp_0
	v_mfma_f32_32x32x16_bf16 v[0:15], v[48:51], v[78:81], v[0:15]
.Lmy_zkp_0:
	ds_read_b128 v[48:51], v76 offset:50944
	ds_read_b128 v[72:75], v76 offset:50976
	s_waitcnt lgkmcnt(1)
	s_cbranch_vccnz .Lmy_zkp_1
	v_mfma_f32_32x32x16_bf16 v[16:31], v[48:51], v[78:81], v[16:31]
.Lmy_zkp_1:
	s_waitcnt vmcnt(6)
	s_cbranch_vccnz .Lmy_zkp_2
	v_mfma_f32_32x32x16_bf16 v[0:15], v[56:59], v[82:85], v[0:15]
.Lmy_zkp_2:
	s_waitcnt lgkmcnt(0)
	s_cbranch_vccnz .Lmy_zkp_3
	v_mfma_f32_32x32x16_bf16 v[16:31], v[72:75], v[82:85], v[16:31]
.Lmy_zkp_3:
	ds_read_b128 v[32:35], v76 offset:34112
	ds_read_b128 v[40:43], v76 offset:34144
	s_waitcnt vmcnt(5) lgkmcnt(1)
	s_cbranch_vccnz .Lmy_zkp_4
	v_mfma_f32_32x32x16_bf16 v[0:15], v[32:35], v[86:89], v[0:15]
.Lmy_zkp_4:
	ds_read_b128 v[32:35], v76 offset:51008
	ds_read_b128 v[48:51], v76 offset:51040
	s_waitcnt lgkmcnt(1)
	s_cbranch_vccnz .Lmy_zkp_5
	v_mfma_f32_32x32x16_bf16 v[16:31], v[32:35], v[86:89], v[16:31]
.Lmy_zkp_5:
	ds_read_b128 v[32:35], v76 offset:34176
	ds_read_b128 v[36:39], v76 offset:34208
	s_waitcnt vmcnt(4)
	s_cbranch_vccnz .Lmy_zkp_6
	v_mfma_f32_32x32x16_bf16 v[0:15], v[40:43], v[90:93], v[0:15]
.Lmy_zkp_6:
	s_waitcnt lgkmcnt(2)
	s_cbranch_vccnz .Lmy_zkp_7
	v_mfma_f32_32x32x16_bf16 v[16:31], v[48:51], v[90:93], v[16:31]
.Lmy_zkp_7:
	s_waitcnt vmcnt(3) lgkmcnt(1)
	s_cbranch_vccnz .Lmy_zkp_8
	v_mfma_f32_32x32x16_bf16 v[0:15], v[32:35], v[100:103], v[0:15]
.Lmy_zkp_8:
	ds_read_b128 v[32:35], v76 offset:51072
	ds_read_b128 v[40:43], v76 offset:51104
	ds_read_b128 v[44:47], v76 offset:34272
	s_waitcnt lgkmcnt(2)
	s_cbranch_vccnz .Lmy_zkp_9
	v_mfma_f32_32x32x16_bf16 v[16:31], v[32:35], v[100:103], v[16:31]
.Lmy_zkp_9:
	s_waitcnt vmcnt(3)
	s_cbranch_vccnz .Lmy_zkp_10
	v_mfma_f32_32x32x16_bf16 v[0:15], v[36:39], v[104:107], v[0:15]
.Lmy_zkp_10:
	ds_read_b128 v[36:39], v76 offset:34240
	s_waitcnt lgkmcnt(2)
	s_cbranch_vccnz .Lmy_zkp_11
	v_mfma_f32_32x32x16_bf16 v[16:31], v[40:43], v[104:107], v[16:31]
.Lmy_zkp_11:
	s_waitcnt vmcnt(3) lgkmcnt(0)
	s_cbranch_vccnz .Lmy_zkp_12
	v_mfma_f32_32x32x16_bf16 v[0:15], v[36:39], v[108:111], v[0:15]
.Lmy_zkp_12:
	ds_read_b128 v[36:39], v76 offset:51136
	ds_read_b128 v[48:51], v76 offset:51168
	s_waitcnt lgkmcnt(1)
	s_cbranch_vccnz .Lmy_zkp_13
	v_mfma_f32_32x32x16_bf16 v[16:31], v[36:39], v[108:111], v[16:31]
.Lmy_zkp_13:
	s_waitcnt vmcnt(3)
	s_cbranch_vccnz .Lmy_zkp_14
	v_mfma_f32_32x32x16_bf16 v[0:15], v[44:47], v[112:115], v[0:15]
.Lmy_zkp_14:
	s_waitcnt lgkmcnt(0)
	s_cbranch_vccnz .Lmy_zkp_15
	v_mfma_f32_32x32x16_bf16 v[16:31], v[48:51], v[112:115], v[16:31]
.Lmy_zkp_15:
	ds_read_b128 v[48:51], v116
	ds_read_b128 v[68:71], v116 offset:32
	s_waitcnt vmcnt(7) lgkmcnt(1)
	v_mfma_f32_32x32x16_bf16 v[0:15], v[48:51], v[168:171], v[0:15]
	ds_read_b128 v[48:51], v116 offset:8704
	ds_read_b128 v[72:75], v116 offset:8736
	s_waitcnt lgkmcnt(1)
	v_mfma_f32_32x32x16_bf16 v[16:31], v[48:51], v[168:171], v[16:31]
	s_waitcnt vmcnt(6)
	v_mfma_f32_32x32x16_bf16 v[0:15], v[68:71], v[172:175], v[0:15]
	s_waitcnt lgkmcnt(0)
	v_mfma_f32_32x32x16_bf16 v[16:31], v[72:75], v[172:175], v[16:31]
	ds_read_b128 v[32:35], v116 offset:64
	ds_read_b128 v[40:43], v116 offset:96
	s_waitcnt vmcnt(5) lgkmcnt(1)
	v_mfma_f32_32x32x16_bf16 v[0:15], v[32:35], v[176:179], v[0:15]
	ds_read_b128 v[32:35], v116 offset:8768
	ds_read_b128 v[48:51], v116 offset:8800
	s_waitcnt lgkmcnt(1)
	v_mfma_f32_32x32x16_bf16 v[16:31], v[32:35], v[176:179], v[16:31]
	ds_read_b128 v[32:35], v116 offset:128
	ds_read_b128 v[36:39], v116 offset:160
	s_waitcnt vmcnt(4)
	v_mfma_f32_32x32x16_bf16 v[0:15], v[40:43], v[180:183], v[0:15]
	s_waitcnt lgkmcnt(2)
	v_mfma_f32_32x32x16_bf16 v[16:31], v[48:51], v[180:183], v[16:31]
	s_waitcnt vmcnt(3) lgkmcnt(1)
	v_mfma_f32_32x32x16_bf16 v[0:15], v[32:35], v[184:187], v[0:15]
	ds_read_b128 v[32:35], v116 offset:8832
	ds_read_b128 v[40:43], v116 offset:8864
	s_waitcnt lgkmcnt(1)
	v_mfma_f32_32x32x16_bf16 v[16:31], v[32:35], v[184:187], v[16:31]
	s_waitcnt vmcnt(2)
	v_mfma_f32_32x32x16_bf16 v[0:15], v[36:39], v[188:191], v[0:15]
	ds_read_b128 v[32:35], v116 offset:192
	ds_read_b128 v[36:39], v116 offset:224
	s_waitcnt lgkmcnt(2)
	v_mfma_f32_32x32x16_bf16 v[16:31], v[40:43], v[188:191], v[16:31]
	s_waitcnt vmcnt(1) lgkmcnt(1)
	v_mfma_f32_32x32x16_bf16 v[0:15], v[32:35], v[192:195], v[0:15]
	ds_read_b128 v[32:35], v116 offset:8896
	ds_read_b128 v[40:43], v116 offset:8928
	s_waitcnt lgkmcnt(1)
	v_mfma_f32_32x32x16_bf16 v[16:31], v[32:35], v[192:195], v[16:31]
	v_lshlrev_b32_e32 v34, 4, v203
	v_and_b32_e32 v116, 16, v34
	s_waitcnt vmcnt(0)
	v_mfma_f32_32x32x16_bf16 v[0:15], v[36:39], v[236:239], v[0:15]
	s_waitcnt lgkmcnt(0)
	v_mfma_f32_32x32x16_bf16 v[16:31], v[40:43], v[236:239], v[16:31]
	s_nop 9
	v_mul_f32_e32 v32, v0, v0
	v_fmamk_f32 v32, v32, 0xbdd2d3e8, v197
	v_mul_f32_e32 v32, v0, v32
	v_exp_f32_e32 v32, v32
	v_mul_f32_e32 v34, v1, v1
	v_fmamk_f32 v34, v34, 0xbdd2d3e8, v197
	v_mul_f32_e32 v34, v1, v34
	v_mul_f32_e32 v33, v16, v16
	v_fmamk_f32 v33, v33, 0xbdd2d3e8, v197
	v_add_f32_e32 v32, 1.0, v32
	v_mul_f32_e32 v33, v16, v33
	v_rcp_f32_e32 v35, v32
	v_exp_f32_e32 v33, v33
	v_exp_f32_e32 v34, v34
	v_mul_f32_e32 v0, v0, v35
	v_mul_f32_e32 v35, v17, v17
	v_add_f32_e32 v32, 1.0, v33
	v_fmamk_f32 v35, v35, 0xbdd2d3e8, v197
	v_rcp_f32_e32 v36, v32
	v_mul_f32_e32 v35, v17, v35
	v_exp_f32_e32 v35, v35
	v_lshl_add_u64 v[32:33], s[24:25], 0, v[116:117]
	v_mul_f32_e32 v16, v16, v36
	v_cvt_pk_bf16_f32 v0, v0, v16
	v_add_f32_e32 v16, 1.0, v34
	v_add_f32_e32 v34, 1.0, v35
	v_rcp_f32_e32 v16, v16
	v_rcp_f32_e32 v34, v34
	ds_write_b16 v198, v0
	ds_write_b16_d16_hi v198, v0 offset:16384
	v_mul_f32_e32 v0, v1, v16
	v_mul_f32_e32 v1, v17, v34
	v_mul_f32_e32 v16, v2, v2
	v_mul_f32_e32 v17, v18, v18
	v_fmamk_f32 v16, v16, 0xbdd2d3e8, v197
	v_fmamk_f32 v17, v17, 0xbdd2d3e8, v197
	v_mul_f32_e32 v16, v2, v16
	v_mul_f32_e32 v17, v18, v17
	v_exp_f32_e32 v16, v16
	v_exp_f32_e32 v17, v17
	v_cvt_pk_bf16_f32 v0, v0, v1
	ds_write_b16 v198, v0 offset:512
	ds_write_b16_d16_hi v198, v0 offset:16896
	v_add_f32_e32 v1, 1.0, v16
	v_add_f32_e32 v16, 1.0, v17
	v_rcp_f32_e32 v1, v1
	v_rcp_f32_e32 v16, v16
	v_mul_f32_e32 v0, v2, v1
	v_mul_f32_e32 v1, v18, v16
	v_mul_f32_e32 v2, v3, v3
	v_mul_f32_e32 v16, v19, v19
	v_fmamk_f32 v2, v2, 0xbdd2d3e8, v197
	v_fmamk_f32 v16, v16, 0xbdd2d3e8, v197
	v_mul_f32_e32 v2, v3, v2
	v_mul_f32_e32 v16, v19, v16
	v_exp_f32_e32 v2, v2
	v_exp_f32_e32 v16, v16
	v_cvt_pk_bf16_f32 v0, v0, v1
	ds_write_b16 v198, v0 offset:1024
	ds_write_b16_d16_hi v198, v0 offset:17408
	v_add_f32_e32 v1, 1.0, v2
	v_add_f32_e32 v2, 1.0, v16
	v_rcp_f32_e32 v1, v1
	v_rcp_f32_e32 v2, v2
	v_mul_f32_e32 v0, v3, v1
	v_mul_f32_e32 v1, v19, v2
	v_mul_f32_e32 v2, v4, v4
	v_mul_f32_e32 v3, v20, v20
	v_fmamk_f32 v2, v2, 0xbdd2d3e8, v197
	v_fmamk_f32 v3, v3, 0xbdd2d3e8, v197
	v_mul_f32_e32 v2, v4, v2
	v_mul_f32_e32 v3, v20, v3
	v_exp_f32_e32 v2, v2
	v_exp_f32_e32 v3, v3
	v_cvt_pk_bf16_f32 v0, v0, v1
	ds_write_b16 v198, v0 offset:1536
	ds_write_b16_d16_hi v198, v0 offset:17920
	v_add_f32_e32 v1, 1.0, v2
	v_add_f32_e32 v2, 1.0, v3
	v_rcp_f32_e32 v1, v1
	v_rcp_f32_e32 v2, v2
	v_mul_f32_e32 v3, v21, v21
	v_fmamk_f32 v3, v3, 0xbdd2d3e8, v197
	v_mul_f32_e32 v0, v4, v1
	v_mul_f32_e32 v1, v20, v2
	v_mul_f32_e32 v2, v5, v5
	v_fmamk_f32 v2, v2, 0xbdd2d3e8, v197
	v_mul_f32_e32 v2, v5, v2
	v_mul_f32_e32 v3, v21, v3
	v_exp_f32_e32 v2, v2
	v_exp_f32_e32 v3, v3
	v_cvt_pk_bf16_f32 v0, v0, v1
	ds_write_b16 v198, v0 offset:4096
	ds_write_b16_d16_hi v198, v0 offset:20480
	v_add_f32_e32 v1, 1.0, v2
	v_add_f32_e32 v2, 1.0, v3
	v_rcp_f32_e32 v1, v1
	v_rcp_f32_e32 v2, v2
	v_mul_f32_e32 v3, v22, v22
	v_fmamk_f32 v3, v3, 0xbdd2d3e8, v197
	v_mul_f32_e32 v0, v5, v1
	v_mul_f32_e32 v1, v21, v2
	v_mul_f32_e32 v2, v6, v6
	v_fmamk_f32 v2, v2, 0xbdd2d3e8, v197
	v_mul_f32_e32 v2, v6, v2
	v_mul_f32_e32 v3, v22, v3
	v_exp_f32_e32 v2, v2
	v_exp_f32_e32 v3, v3
	v_cvt_pk_bf16_f32 v0, v0, v1
	ds_write_b16 v198, v0 offset:4608
	ds_write_b16_d16_hi v198, v0 offset:20992
	v_add_f32_e32 v1, 1.0, v2
	v_add_f32_e32 v2, 1.0, v3
	v_rcp_f32_e32 v1, v1
	v_rcp_f32_e32 v2, v2
	v_mul_f32_e32 v3, v23, v23
	v_fmamk_f32 v3, v3, 0xbdd2d3e8, v197
	v_mul_f32_e32 v0, v6, v1
	v_mul_f32_e32 v1, v22, v2
	v_mul_f32_e32 v2, v7, v7
	v_fmamk_f32 v2, v2, 0xbdd2d3e8, v197
	v_mul_f32_e32 v2, v7, v2
	v_mul_f32_e32 v3, v23, v3
	v_exp_f32_e32 v2, v2
	v_exp_f32_e32 v3, v3
	v_cvt_pk_bf16_f32 v0, v0, v1
	ds_write_b16 v198, v0 offset:5120
	ds_write_b16_d16_hi v198, v0 offset:21504
	v_add_f32_e32 v1, 1.0, v2
	v_add_f32_e32 v2, 1.0, v3
	v_rcp_f32_e32 v1, v1
	v_rcp_f32_e32 v2, v2
	v_mul_f32_e32 v3, v24, v24
	v_fmamk_f32 v3, v3, 0xbdd2d3e8, v197
	v_mul_f32_e32 v0, v7, v1
	v_mul_f32_e32 v1, v23, v2
	v_mul_f32_e32 v2, v8, v8
	v_fmamk_f32 v2, v2, 0xbdd2d3e8, v197
	v_mul_f32_e32 v2, v8, v2
	v_mul_f32_e32 v3, v24, v3
	v_exp_f32_e32 v2, v2
	v_exp_f32_e32 v3, v3
	v_cvt_pk_bf16_f32 v0, v0, v1
	ds_write_b16 v198, v0 offset:5632
	ds_write_b16_d16_hi v198, v0 offset:22016
	v_add_f32_e32 v1, 1.0, v2
	v_add_f32_e32 v2, 1.0, v3
	v_rcp_f32_e32 v1, v1
	v_rcp_f32_e32 v2, v2
	v_mul_f32_e32 v3, v25, v25
	v_fmamk_f32 v3, v3, 0xbdd2d3e8, v197
	v_mul_f32_e32 v0, v8, v1
	v_mul_f32_e32 v1, v24, v2
	v_mul_f32_e32 v2, v9, v9
	v_fmamk_f32 v2, v2, 0xbdd2d3e8, v197
	v_mul_f32_e32 v2, v9, v2
	v_mul_f32_e32 v3, v25, v3
	v_exp_f32_e32 v2, v2
	v_exp_f32_e32 v3, v3
	v_cvt_pk_bf16_f32 v0, v0, v1
	ds_write_b16 v198, v0 offset:8192
	ds_write_b16_d16_hi v198, v0 offset:24576
	v_add_f32_e32 v1, 1.0, v2
	v_add_f32_e32 v2, 1.0, v3
	v_rcp_f32_e32 v1, v1
	v_rcp_f32_e32 v2, v2
	v_mul_f32_e32 v3, v26, v26
	v_fmamk_f32 v3, v3, 0xbdd2d3e8, v197
	v_mul_f32_e32 v0, v9, v1
	v_mul_f32_e32 v1, v25, v2
	v_mul_f32_e32 v2, v10, v10
	v_fmamk_f32 v2, v2, 0xbdd2d3e8, v197
	v_mul_f32_e32 v2, v10, v2
	v_mul_f32_e32 v3, v26, v3
	v_exp_f32_e32 v2, v2
	v_exp_f32_e32 v3, v3
	v_cvt_pk_bf16_f32 v0, v0, v1
	ds_write_b16 v198, v0 offset:8704
	ds_write_b16_d16_hi v198, v0 offset:25088
	v_add_f32_e32 v1, 1.0, v2
	v_add_f32_e32 v2, 1.0, v3
	v_rcp_f32_e32 v1, v1
	v_rcp_f32_e32 v2, v2
	v_mul_f32_e32 v3, v27, v27
	v_fmamk_f32 v3, v3, 0xbdd2d3e8, v197
	v_mul_f32_e32 v0, v10, v1
	v_mul_f32_e32 v1, v26, v2
	v_mul_f32_e32 v2, v11, v11
	v_fmamk_f32 v2, v2, 0xbdd2d3e8, v197
	v_mul_f32_e32 v2, v11, v2
	v_mul_f32_e32 v3, v27, v3
	v_exp_f32_e32 v2, v2
	v_exp_f32_e32 v3, v3
	v_cvt_pk_bf16_f32 v0, v0, v1
	ds_write_b16 v198, v0 offset:9216
	ds_write_b16_d16_hi v198, v0 offset:25600
	v_add_f32_e32 v1, 1.0, v2
	v_add_f32_e32 v2, 1.0, v3
	v_rcp_f32_e32 v1, v1
	v_rcp_f32_e32 v2, v2
	v_mul_f32_e32 v3, v28, v28
	v_fmamk_f32 v3, v3, 0xbdd2d3e8, v197
	v_mul_f32_e32 v0, v11, v1
	v_mul_f32_e32 v1, v27, v2
	v_mul_f32_e32 v2, v12, v12
	v_fmamk_f32 v2, v2, 0xbdd2d3e8, v197
	v_mul_f32_e32 v2, v12, v2
	v_mul_f32_e32 v3, v28, v3
	v_exp_f32_e32 v2, v2
	v_exp_f32_e32 v3, v3
	v_cvt_pk_bf16_f32 v0, v0, v1
	ds_write_b16 v198, v0 offset:9728
	ds_write_b16_d16_hi v198, v0 offset:26112
	v_add_f32_e32 v1, 1.0, v2
	v_add_f32_e32 v2, 1.0, v3
	v_rcp_f32_e32 v1, v1
	v_rcp_f32_e32 v2, v2
	v_mul_f32_e32 v3, v29, v29
	v_fmamk_f32 v3, v3, 0xbdd2d3e8, v197
	v_mul_f32_e32 v0, v12, v1
	v_mul_f32_e32 v1, v28, v2
	v_mul_f32_e32 v2, v13, v13
	v_fmamk_f32 v2, v2, 0xbdd2d3e8, v197
	v_mul_f32_e32 v2, v13, v2
	v_mul_f32_e32 v3, v29, v3
	v_exp_f32_e32 v2, v2
	v_exp_f32_e32 v3, v3
	v_cvt_pk_bf16_f32 v0, v0, v1
	ds_write_b16 v198, v0 offset:12288
	ds_write_b16_d16_hi v198, v0 offset:28672
	v_add_f32_e32 v1, 1.0, v2
	v_add_f32_e32 v2, 1.0, v3
	v_rcp_f32_e32 v1, v1
	v_rcp_f32_e32 v2, v2
	v_mul_f32_e32 v3, v30, v30
	v_fmamk_f32 v3, v3, 0xbdd2d3e8, v197
	v_mul_f32_e32 v0, v13, v1
	v_mul_f32_e32 v1, v29, v2
	v_mul_f32_e32 v2, v14, v14
	v_fmamk_f32 v2, v2, 0xbdd2d3e8, v197
	v_mul_f32_e32 v2, v14, v2
	v_mul_f32_e32 v3, v30, v3
	v_exp_f32_e32 v2, v2
	v_exp_f32_e32 v3, v3
	v_cvt_pk_bf16_f32 v0, v0, v1
	ds_write_b16 v198, v0 offset:12800
	ds_write_b16_d16_hi v198, v0 offset:29184
	v_add_f32_e32 v1, 1.0, v2
	v_add_f32_e32 v2, 1.0, v3
	v_rcp_f32_e32 v1, v1
	v_rcp_f32_e32 v2, v2
	v_mul_f32_e32 v3, v31, v31
	v_fmamk_f32 v3, v3, 0xbdd2d3e8, v197
	v_mul_f32_e32 v0, v14, v1
	v_mul_f32_e32 v1, v30, v2
	v_mul_f32_e32 v2, v15, v15
	v_fmamk_f32 v2, v2, 0xbdd2d3e8, v197
	v_mul_f32_e32 v2, v15, v2
	v_exp_f32_e32 v2, v2
	v_mul_f32_e32 v3, v31, v3
	v_exp_f32_e32 v3, v3
	v_cvt_pk_bf16_f32 v0, v0, v1
	v_add_f32_e32 v1, 1.0, v2
	v_rcp_f32_e32 v1, v1
	v_add_f32_e32 v2, 1.0, v3
	v_rcp_f32_e32 v2, v2
	ds_write_b16 v198, v0 offset:13312
	ds_write_b16_d16_hi v198, v0 offset:29696
	v_mul_f32_e32 v0, v15, v1
	v_lshlrev_b64 v[4:5], 11, v[124:125]
	v_mul_f32_e32 v1, v31, v2
	v_cvt_pk_bf16_f32 v0, v0, v1
	ds_write_b16 v198, v0 offset:13824
	ds_write_b16_d16_hi v198, v0 offset:30208
	s_waitcnt lgkmcnt(0)
	s_barrier
	ds_read_b128 v[0:3], v202
	v_lshl_add_u64 v[4:5], v[32:33], 0, v[4:5]
	v_add_co_u32_e32 v8, vcc, s35, v4
	s_nop 1
	v_addc_co_u32_e32 v9, vcc, 0, v5, vcc
	ds_read_b128 v[4:7], v201
	s_waitcnt lgkmcnt(1)
	global_store_dwordx4 v[8:9], v[0:3], off
	s_nop 1
	v_lshlrev_b64 v[0:1], 11, v[122:123]
	v_lshl_add_u64 v[0:1], v[32:33], 0, v[0:1]
	v_add_co_u32_e32 v0, vcc, s35, v0
	s_nop 1
	v_addc_co_u32_e32 v1, vcc, 0, v1, vcc
	s_waitcnt lgkmcnt(0)
	global_store_dwordx4 v[0:1], v[4:7], off
	ds_read_b128 v[0:3], v200
	s_nop 0
	v_lshlrev_b64 v[4:5], 11, v[120:121]
	v_lshl_add_u64 v[4:5], v[32:33], 0, v[4:5]
	v_add_co_u32_e32 v8, vcc, s35, v4
	s_nop 1
	v_addc_co_u32_e32 v9, vcc, 0, v5, vcc
	ds_read_b128 v[4:7], v199
	s_waitcnt lgkmcnt(1)
	global_store_dwordx4 v[8:9], v[0:3], off
	s_nop 1
	v_lshlrev_b64 v[0:1], 11, v[118:119]
	v_lshl_add_u64 v[0:1], v[32:33], 0, v[0:1]
	v_add_co_u32_e32 v0, vcc, 0xe00000, v0
	s_nop 1
	v_addc_co_u32_e32 v1, vcc, 0, v1, vcc
	s_waitcnt lgkmcnt(0)
	global_store_dwordx4 v[0:1], v[4:7], off
	s_barrier
	s_waitcnt vmcnt(0)
	s_barrier
	s_mov_b64 s[78:79], exec
	v_readlane_b32 s24, v253, 3
	v_readlane_b32 s25, v253, 4
	s_and_b64 s[24:25], s[78:79], s[24:25]
	s_mov_b64 s[82:83], s[72:73]
	s_mov_b64 exec, s[24:25]
	s_cbranch_execz .LBB0_622
	s_mov_b64 s[80:81], exec
	v_mbcnt_lo_u32_b32 v0, s80, 0
	buffer_wbl2 sc1
	s_waitcnt vmcnt(0)
	s_waitcnt vmcnt(0)
	v_mbcnt_hi_u32_b32 v0, s81, v0
	v_cmp_eq_u32_e32 vcc, 0, v0
	s_and_b64 s[24:25], exec, vcc
	s_mov_b64 exec, s[24:25]
	s_cbranch_execz .LBB0_622
	s_bcnt1_i32_b64 s2, s[80:81]
	v_mov_b32_e32 v0, s2
	global_atomic_add v117, v0, s[42:43]
	s_branch .LBB0_622
